# FFN-down / D_out patch loops: closed-form unit order (no division sequence), no store drain between units
# baseline (speedup 1.0000x reference)
;     __device__ bool next(int i, Unit& u) const {
;         const long L = (long)i * G + c; if (L >= nwg) return false;
;         int wgid = (int)L; { const int q = nwg / NXCD, r = nwg % NXCD, xcd = wgid % NXCD, off = wgid / NXCD; wgid = (xcd < r ? xcd * (q + 1) : r * (q + 1) + (xcd - r) * q) + off; }
;         const int nig = wgm * nN, gid = wgid / nig, fm = gid * wgm, gsz = (nM - fm) < wgm ? (nM - fm) : wgm;
;         u.pm = fm + ((wgid % nig) % gsz); u.pn = (wgid % nig) / gsz; return true;
;     }
.LBB0_240:
	v_cmp_gt_i64_e32 vcc, s[8:9], v[246:247]
	s_cbranch_vccnz .LBB0_246
	s_and_b32 s0, s8, 7
	s_lshr_b32 s1, s8, 3
	s_lshl_b32 s0, s0, 6
	s_add_i32 s0, s0, s1
	s_lshr_b32 s3, s0, 5
	s_lshl_b32 s3, s3, 3
	s_and_b32 s0, s0, 7
	s_add_i32 s3, s3, s0

;     __device__ bool next(int i, Unit& u) const {
;         const long L = (long)i * G + c; if (L >= nwg) return false;
;         int wgid = (int)L; { const int q = nwg / NXCD, r = nwg % NXCD, xcd = wgid % NXCD, off = wgid / NXCD; wgid = (xcd < r ? xcd * (q + 1) : r * (q + 1) + (xcd - r) * q) + off; }
;         const int nig = wgm * nN, gid = wgid / nig, fm = gid * wgm, gsz = (nM - fm) < wgm ? (nM - fm) : wgm;
;         u.pm = fm + ((wgid % nig) % gsz); u.pn = (wgid % nig) / gsz; return true;
; __global__ void __launch_bounds__(NTHREADS) mega_fwd(Params p) {
;     ...
;                 const float* ZS = (const float*)(AR + 176 * MiB); bf16_t* A2 = (bf16_t*)AR; const float* cw = p.in[31] + (size_t)fl * 3 * 5632; const float* cb = p.in[32] + (size_t)fl * 5632;
;                 pg8::Unit uu;
;                 for (int i = 0; S.next(i, uu); ++i) { if ((uu.pm & 15) == 0) continue;
;                     for (int idx = tid; idx < 2 * 704; idx += NTHREADS) { const int r = idx / 704, c = (idx - r * 704) * 4;
;                         f32x4 gsum = *(const f32x4*)(cb + c), vsum = *(const f32x4*)(cb + FFW + c);
; #pragma unroll
;                         for (int k = 0; k < 3; ++k) { const int j = r - 2 + k; const float* zr = (j < 0) ? ZS + ((size_t)(uu.pm - 1) * 4 + 4 + j) * 5632 : ZS + ((size_t)uu.pm * 4 + j) * 5632;
;                             gsum += *(const f32x4*)(cw + k * 5632 + c) * *(const f32x4*)(zr + c); vsum += *(const f32x4*)(cw + k * 5632 + FFW + c) * *(const f32x4*)(zr + FFW + c); }
.LBB0_254:
	s_mul_i32 s0, s42, s95
	s_mul_hi_u32 s1, s42, s72
	s_add_i32 s1, s1, s0
	s_mul_i32 s0, s42, s72
	s_add_u32 s36, s0, s84
	s_addc_u32 s37, s1, s11
	v_cmp_gt_i64_e32 vcc, s[36:37], v[246:247]
	s_cbranch_vccnz .LBB0_260
	s_and_b32 s0, s36, 7
	s_lshr_b32 s1, s36, 3
	s_lshl_b32 s0, s0, 6
	s_add_i32 s0, s0, s1
	s_lshr_b32 s8, s0, 5
	s_lshl_b32 s8, s8, 3
	s_and_b32 s0, s0, 7
	s_add_i32 s8, s8, s0
.LBB0_260:
	v_mov_b64_e32 v[2:3], 0x200
	v_cmp_lt_i64_e32 vcc, s[36:37], v[2:3]
	s_mov_b64 s[0:1], -1
	s_cbranch_vccz .LBB0_253
	s_and_b32 s0, s8, 15
	s_cmp_lg_u32 s0, 0
	s_cselect_b64 s[0:1], -1, 0
	s_and_b64 s[0:1], s[0:1], s[34:35]
	s_and_saveexec_b64 s[36:37], s[0:1]
	s_cbranch_execz .LBB0_252
	s_ashr_i32 s9, s8, 31
	s_lshl_b64 s[38:39], s[8:9], 2
	s_lshl_b32 s9, s8, 8
	s_mov_b64 s[40:41], 0
	v_mov_b32_e32 v50, v251
	v_add_u32_e32 v130, 0x200, v251
	v_add_u32_e32 v210, 0x400, v251
	v_mov_b32_e32 v81, 0
	v_mov_b32_e32 v161, 0
	s_mov_b32 s0, 0x2e8ba2e9
	v_mul_hi_i32 v0, v50, s0
	v_lshrrev_b32_e32 v2, 31, v0
	v_ashrrev_i32_e32 v0, 7, v0
	v_add_u32_e32 v44, v0, v2
	v_add_u32_e32 v10, -2, v44
	v_mul_i32_i24_e32 v0, 0xfffffd40, v44
	v_ashrrev_i32_e32 v11, 31, v10
	v_add_lshl_u32 v42, v0, v50, 2
	v_lshl_add_u64 v[10:11], s[38:39], 0, v[10:11]
	v_mov_b64_e32 v[12:13], s[4:5]
	v_ashrrev_i32_e32 v43, 31, v42
	v_mad_u64_u32 v[14:15], s[0:1], v10, s76, v[12:13]
	v_lshlrev_b64 v[46:47], 2, v[42:43]
	v_mad_i32_i24 v15, v11, s76, v15
	v_lshl_add_u64 v[2:3], s[18:19], 0, v[46:47]
	v_lshl_add_u64 v[4:5], s[20:21], 0, v[46:47]
	v_lshl_add_u64 v[22:23], v[14:15], 0, v[46:47]
	global_load_dwordx4 v[6:9], v[2:3], off
	s_nop 0
	global_load_dwordx4 v[2:5], v[4:5], off
	v_lshl_add_u64 v[10:11], s[16:17], 0, v[46:47]
	global_load_dwordx4 v[14:17], v[22:23], off
	v_add_co_u32_e32 v22, vcc, 0x2000, v22
	v_lshl_add_u64 v[18:19], s[22:23], 0, v[46:47]
	s_nop 0
	v_addc_co_u32_e32 v23, vcc, 0, v23, vcc
	global_load_dwordx4 v[10:13], v[10:11], off
	s_movk_i32 s0, 0x2bf
	global_load_dwordx4 v[18:21], v[18:19], off
	v_add_u32_e32 v0, -1, v44
	global_load_dwordx4 v[22:25], v[22:23], off offset:3072
	v_cmp_lt_i32_e32 vcc, s0, v50
	s_and_saveexec_b64 s[0:1], vcc
	s_xor_b64 s[0:1], exec, s[0:1]
	v_lshl_add_u64 v[26:27], s[38:39], 0, v[0:1]
	s_andn2_saveexec_b64 s[0:1], s[0:1]
	v_ashrrev_i32_e32 v27, 31, v0
	v_mov_b32_e32 v26, v0
	v_lshl_add_u64 v[26:27], s[38:39], 0, v[26:27]
	s_or_b64 exec, exec, s[0:1]
	v_mov_b64_e32 v[28:29], s[4:5]
	v_mad_u64_u32 v[30:31], s[0:1], v26, s76, v[28:29]
	v_mov_b32_e32 v0, v31
	v_mad_u64_u32 v[26:27], s[0:1], v27, s76, v[0:1]
	v_mov_b32_e32 v31, v26
	v_lshl_add_u64 v[38:39], v[30:31], 0, v[46:47]
	global_load_dwordx4 v[30:33], v[38:39], off
	v_add_co_u32_e32 v38, vcc, 0x2000, v38
	v_lshl_add_u64 v[26:27], s[24:25], 0, v[46:47]
	v_lshl_add_u64 v[34:35], s[26:27], 0, v[46:47]
	v_addc_co_u32_e32 v39, vcc, 0, v39, vcc
	global_load_dwordx4 v[26:29], v[26:27], off
	s_movk_i32 s0, 0xfd40
	global_load_dwordx4 v[34:37], v[34:35], off
	v_cmp_lt_i32_e32 vcc, s0, v50
	global_load_dwordx4 v[38:41], v[38:39], off offset:3072
	s_and_saveexec_b64 s[0:1], vcc
	s_xor_b64 s[0:1], exec, s[0:1]
	v_mov_b32_e32 v45, v1
	v_lshl_add_u64 v[48:49], s[38:39], 0, v[44:45]
	s_andn2_saveexec_b64 s[0:1], s[0:1]
	v_ashrrev_i32_e32 v45, 31, v44
	v_lshl_add_u64 v[48:49], s[38:39], 0, v[44:45]
	s_or_b64 exec, exec, s[0:1]
	v_mov_b64_e32 v[52:53], s[4:5]
	v_mad_u64_u32 v[54:55], s[0:1], v48, s76, v[52:53]
	v_mov_b32_e32 v0, v55
	v_mad_u64_u32 v[52:53], s[0:1], v49, s76, v[0:1]
	v_mov_b32_e32 v55, v52
	v_lshl_add_u64 v[56:57], s[28:29], 0, v[46:47]
	v_lshl_add_u64 v[54:55], v[54:55], 0, v[46:47]
	global_load_dwordx4 v[60:63], v[56:57], off
	v_add_co_u32_e32 v52, vcc, s63, v54
	v_lshl_add_u64 v[56:57], s[30:31], 0, v[46:47]
	global_load_dwordx4 v[64:67], v[54:55], off
	v_addc_co_u32_e32 v53, vcc, 0, v55, vcc
	global_load_dwordx4 v[68:71], v[56:57], off
	global_load_dwordx4 v[72:75], v[52:53], off offset:3072
	s_mov_b32 s0, 0x2e8ba2e9
	v_mul_hi_i32 v80, v130, s0
	v_lshrrev_b32_e32 v82, 31, v80
	v_ashrrev_i32_e32 v80, 7, v80
	v_add_u32_e32 v124, v80, v82
	v_add_u32_e32 v90, -2, v124
	v_mul_i32_i24_e32 v80, 0xfffffd40, v124
	v_ashrrev_i32_e32 v91, 31, v90
	v_add_lshl_u32 v122, v80, v130, 2
	v_lshl_add_u64 v[90:91], s[38:39], 0, v[90:91]
	v_mov_b64_e32 v[92:93], s[4:5]
	v_ashrrev_i32_e32 v123, 31, v122
	v_mad_u64_u32 v[94:95], s[0:1], v90, s76, v[92:93]
	v_lshlrev_b64 v[126:127], 2, v[122:123]
	v_mad_i32_i24 v95, v91, s76, v95
	v_lshl_add_u64 v[82:83], s[18:19], 0, v[126:127]
	v_lshl_add_u64 v[84:85], s[20:21], 0, v[126:127]
	v_lshl_add_u64 v[102:103], v[94:95], 0, v[126:127]
	global_load_dwordx4 v[86:89], v[82:83], off
	s_nop 0
	global_load_dwordx4 v[82:85], v[84:85], off
	v_lshl_add_u64 v[90:91], s[16:17], 0, v[126:127]
	global_load_dwordx4 v[94:97], v[102:103], off
	v_add_co_u32_e32 v102, vcc, 0x2000, v102
	v_lshl_add_u64 v[98:99], s[22:23], 0, v[126:127]
	s_nop 0
	v_addc_co_u32_e32 v103, vcc, 0, v103, vcc
	global_load_dwordx4 v[90:93], v[90:91], off
	s_movk_i32 s0, 0x2bf
	global_load_dwordx4 v[98:101], v[98:99], off
	v_add_u32_e32 v80, -1, v124
	global_load_dwordx4 v[102:105], v[102:103], off offset:3072
	v_cmp_lt_i32_e32 vcc, s0, v130
	s_and_saveexec_b64 s[0:1], vcc
; __global__ void __launch_bounds__(NTHREADS) mega_fwd(Params p) {
;     ...
;                     for (int idx = tid; idx < 2 * 704; idx += NTHREADS) { const int r = idx / 704, c = (idx - r * 704) * 4;
;                         f32x4 gsum = *(const f32x4*)(cb + c), vsum = *(const f32x4*)(cb + FFW + c);
; #pragma unroll
;                         for (int k = 0; k < 3; ++k) { const int j = r - 2 + k; const float* zr = (j < 0) ? ZS + ((size_t)(uu.pm - 1) * 4 + 4 + j) * 5632 : ZS + ((size_t)uu.pm * 4 + j) * 5632;
;                             gsum += *(const f32x4*)(cw + k * 5632 + c) * *(const f32x4*)(zr + c); vsum += *(const f32x4*)(cw + k * 5632 + FFW + c) * *(const f32x4*)(zr + FFW + c); }
	s_xor_b64 s[0:1], exec, s[0:1]
	v_lshl_add_u64 v[106:107], s[38:39], 0, v[80:81]
	s_andn2_saveexec_b64 s[0:1], s[0:1]
	v_ashrrev_i32_e32 v107, 31, v80
	v_mov_b32_e32 v106, v80
	v_lshl_add_u64 v[106:107], s[38:39], 0, v[106:107]
	s_or_b64 exec, exec, s[0:1]
	v_mov_b64_e32 v[108:109], s[4:5]
	v_mad_u64_u32 v[110:111], s[0:1], v106, s76, v[108:109]
	v_mov_b32_e32 v80, v111
	v_mad_u64_u32 v[106:107], s[0:1], v107, s76, v[80:81]
	v_mov_b32_e32 v111, v106
	v_lshl_add_u64 v[118:119], v[110:111], 0, v[126:127]
	global_load_dwordx4 v[110:113], v[118:119], off
	v_add_co_u32_e32 v118, vcc, 0x2000, v118
	v_lshl_add_u64 v[106:107], s[24:25], 0, v[126:127]
	v_lshl_add_u64 v[114:115], s[26:27], 0, v[126:127]
	v_addc_co_u32_e32 v119, vcc, 0, v119, vcc
	global_load_dwordx4 v[106:109], v[106:107], off
	s_movk_i32 s0, 0xfd40
	global_load_dwordx4 v[114:117], v[114:115], off
	v_cmp_lt_i32_e32 vcc, s0, v130
	global_load_dwordx4 v[118:121], v[118:119], off offset:3072
	s_and_saveexec_b64 s[0:1], vcc
	s_xor_b64 s[0:1], exec, s[0:1]
	v_mov_b32_e32 v125, v1
	v_lshl_add_u64 v[128:129], s[38:39], 0, v[124:125]
	s_andn2_saveexec_b64 s[0:1], s[0:1]
	v_ashrrev_i32_e32 v125, 31, v124
	v_lshl_add_u64 v[128:129], s[38:39], 0, v[124:125]
	s_or_b64 exec, exec, s[0:1]
	v_mov_b64_e32 v[132:133], s[4:5]
	v_mad_u64_u32 v[134:135], s[0:1], v128, s76, v[132:133]
	v_mov_b32_e32 v80, v135
	v_mad_u64_u32 v[132:133], s[0:1], v129, s76, v[80:81]
	v_mov_b32_e32 v135, v132
	v_lshl_add_u64 v[136:137], s[28:29], 0, v[126:127]
	v_lshl_add_u64 v[134:135], v[134:135], 0, v[126:127]
	global_load_dwordx4 v[140:143], v[136:137], off
	v_add_co_u32_e32 v132, vcc, s63, v134
	v_lshl_add_u64 v[136:137], s[30:31], 0, v[126:127]
	global_load_dwordx4 v[144:147], v[134:135], off
	v_addc_co_u32_e32 v133, vcc, 0, v135, vcc
	global_load_dwordx4 v[148:151], v[136:137], off
	global_load_dwordx4 v[152:155], v[132:133], off offset:3072
	v_cmp_gt_i32_e32 vcc, 0x580, v210
	s_and_saveexec_b64 s[40:41], vcc
	s_cbranch_execz .Lpatch_l2
	s_mov_b32 s0, 0x2e8ba2e9
	v_mul_hi_i32 v160, v210, s0
	v_lshrrev_b32_e32 v162, 31, v160
	v_ashrrev_i32_e32 v160, 7, v160
	v_add_u32_e32 v204, v160, v162
	v_add_u32_e32 v170, -2, v204
	v_mul_i32_i24_e32 v160, 0xfffffd40, v204
	v_ashrrev_i32_e32 v171, 31, v170
	v_add_lshl_u32 v202, v160, v210, 2
	v_lshl_add_u64 v[170:171], s[38:39], 0, v[170:171]
	v_mov_b64_e32 v[172:173], s[4:5]
	v_ashrrev_i32_e32 v203, 31, v202
	v_mad_u64_u32 v[174:175], s[0:1], v170, s76, v[172:173]
	v_lshlrev_b64 v[206:207], 2, v[202:203]
	v_mad_i32_i24 v175, v171, s76, v175
	v_lshl_add_u64 v[162:163], s[18:19], 0, v[206:207]
	v_lshl_add_u64 v[164:165], s[20:21], 0, v[206:207]
	v_lshl_add_u64 v[182:183], v[174:175], 0, v[206:207]
	global_load_dwordx4 v[166:169], v[162:163], off
	s_nop 0
	global_load_dwordx4 v[162:165], v[164:165], off
	v_lshl_add_u64 v[170:171], s[16:17], 0, v[206:207]
	global_load_dwordx4 v[174:177], v[182:183], off
	v_add_co_u32_e32 v182, vcc, 0x2000, v182
	v_lshl_add_u64 v[178:179], s[22:23], 0, v[206:207]
	s_nop 0
	v_addc_co_u32_e32 v183, vcc, 0, v183, vcc
	global_load_dwordx4 v[170:173], v[170:171], off
	s_movk_i32 s0, 0x2bf
	global_load_dwordx4 v[178:181], v[178:179], off
	v_add_u32_e32 v160, -1, v204
	global_load_dwordx4 v[182:185], v[182:183], off offset:3072
	v_cmp_lt_i32_e32 vcc, s0, v210
	s_and_saveexec_b64 s[0:1], vcc
	s_xor_b64 s[0:1], exec, s[0:1]
	v_lshl_add_u64 v[186:187], s[38:39], 0, v[160:161]
	s_andn2_saveexec_b64 s[0:1], s[0:1]
	v_ashrrev_i32_e32 v187, 31, v160
	v_mov_b32_e32 v186, v160
	v_lshl_add_u64 v[186:187], s[38:39], 0, v[186:187]
	s_or_b64 exec, exec, s[0:1]
	v_mov_b64_e32 v[188:189], s[4:5]
	v_mad_u64_u32 v[190:191], s[0:1], v186, s76, v[188:189]
	v_mov_b32_e32 v160, v191
	v_mad_u64_u32 v[186:187], s[0:1], v187, s76, v[160:161]
	v_mov_b32_e32 v191, v186
	v_lshl_add_u64 v[198:199], v[190:191], 0, v[206:207]
	global_load_dwordx4 v[190:193], v[198:199], off
	v_add_co_u32_e32 v198, vcc, 0x2000, v198
	v_lshl_add_u64 v[186:187], s[24:25], 0, v[206:207]
	v_lshl_add_u64 v[194:195], s[26:27], 0, v[206:207]
	v_addc_co_u32_e32 v199, vcc, 0, v199, vcc
	global_load_dwordx4 v[186:189], v[186:187], off
	s_movk_i32 s0, 0xfd40
	global_load_dwordx4 v[194:197], v[194:195], off
	v_cmp_lt_i32_e32 vcc, s0, v210
	global_load_dwordx4 v[198:201], v[198:199], off offset:3072
	s_and_saveexec_b64 s[0:1], vcc
	s_xor_b64 s[0:1], exec, s[0:1]
	v_mov_b32_e32 v205, v1
	v_lshl_add_u64 v[208:209], s[38:39], 0, v[204:205]
	s_andn2_saveexec_b64 s[0:1], s[0:1]
	v_ashrrev_i32_e32 v205, 31, v204
	v_lshl_add_u64 v[208:209], s[38:39], 0, v[204:205]
	s_or_b64 exec, exec, s[0:1]
	v_mov_b64_e32 v[212:213], s[4:5]
	v_mad_u64_u32 v[214:215], s[0:1], v208, s76, v[212:213]
	v_mov_b32_e32 v160, v215
	v_mad_u64_u32 v[212:213], s[0:1], v209, s76, v[160:161]
	v_mov_b32_e32 v215, v212
	v_lshl_add_u64 v[216:217], s[28:29], 0, v[206:207]
	v_lshl_add_u64 v[214:215], v[214:215], 0, v[206:207]
	global_load_dwordx4 v[220:223], v[216:217], off
	v_add_co_u32_e32 v212, vcc, s63, v214
	v_lshl_add_u64 v[216:217], s[30:31], 0, v[206:207]
	global_load_dwordx4 v[224:227], v[214:215], off
	v_addc_co_u32_e32 v213, vcc, 0, v215, vcc
	global_load_dwordx4 v[228:231], v[216:217], off
	global_load_dwordx4 v[232:235], v[212:213], off offset:3072
